# weight conversion re-scheduled: layer-0 down-proj weights converted in the up-projection idle slot, layer-1 down-proj weights in the layer-1 input-projection idle slot
# speedup vs baseline: 1.0188x; 1.0188x over previous
.LBB0_680:
	v_readlane_b32 s2, v253, 46
	v_readlane_b32 s3, v253, 47
	s_and_b64 s[2:3], s[2:3], s[74:75]
	v_writelane_b32 v254, s2, 57
	s_nop 1
	v_writelane_b32 v254, s3, 58
	v_readlane_b32 s2, v253, 46
	v_readlane_b32 s3, v253, 47
	s_xor_b64 s[2:3], s[2:3], -1
	s_cmp_lt_i32 s24, 64
	s_cselect_b64 s[4:5], -1, 0
	s_or_b64 s[2:3], s[2:3], s[4:5]
	s_and_b64 vcc, exec, s[2:3]
	s_cbranch_vccnz .LBB0_945
	s_mul_i32 s2, s25, 0x2200
	s_add_i32 s9, s2, 0
	s_lshl_b32 s2, s24, 3
	v_and_b32_e32 v0, 63, v138
	s_add_i32 s2, s25, s2
	s_add_i32 s8, s2, 0xfffffe00
	v_lshrrev_b32_e32 v8, 5, v0
	v_lshlrev_b32_e32 v1, 2, v138
	v_lshrrev_b32_e32 v9, 3, v0
	v_lshlrev_b32_e32 v2, 3, v0
	s_cmpk_gt_i32 s8, 0x7ff
	v_and_b32_e32 v0, 0x7c, v1
	v_mul_u32_u24_e32 v10, 0x84, v8
	v_and_b32_e32 v12, 56, v2
	v_lshlrev_b32_e32 v11, 2, v9
	s_waitcnt vmcnt(0)
	s_barrier
	s_cmp_eq_u64 s[74:75], 0
	s_cbranch_scc1 .LBB0_942
	s_cmpk_gt_i32 s8, 0x7ff
	s_cbranch_scc1 .LBB0_939
	v_readlane_b32 s12, v253, 23
	v_readlane_b32 s2, v254, 5
	v_mov_b32_e32 v1, v177
	v_readlane_b32 s18, v253, 29
	v_readlane_b32 s19, v253, 30
	v_add_u32_e32 v6, s9, v0
	v_mul_u32_u24_e32 v7, 0x84, v12
	v_lshlrev_b32_e32 v176, 1, v12
	v_readlane_b32 s3, v254, 6
	v_lshl_add_u64 v[2:3], s[18:19], 0, v[0:1]
	v_or_b32_e32 v1, 2, v8
	v_or_b32_e32 v13, 4, v8
	v_or_b32_e32 v14, 6, v8
	v_or_b32_e32 v15, 8, v8
	v_or_b32_e32 v16, 10, v8
	v_or_b32_e32 v17, 12, v8
	v_or_b32_e32 v18, 14, v8
	v_or_b32_e32 v19, 16, v8
	v_or_b32_e32 v20, 18, v8
	v_or_b32_e32 v21, 20, v8
	v_or_b32_e32 v22, 22, v8
	v_or_b32_e32 v23, 24, v8
	v_or_b32_e32 v24, 26, v8
	v_or_b32_e32 v25, 28, v8
	v_or_b32_e32 v26, 30, v8
	v_or_b32_e32 v27, 32, v8
	v_or_b32_e32 v28, 34, v8
	v_or_b32_e32 v29, 36, v8
	v_or_b32_e32 v30, 38, v8
	v_or_b32_e32 v31, 40, v8
	v_or_b32_e32 v32, 42, v8
	v_or_b32_e32 v33, 44, v8
	v_or_b32_e32 v34, 46, v8
	v_or_b32_e32 v35, 48, v8
	v_or_b32_e32 v36, 50, v8
	v_or_b32_e32 v37, 52, v8
	v_or_b32_e32 v38, 54, v8
	v_or_b32_e32 v39, 56, v8
	v_or_b32_e32 v40, 58, v8
	v_or_b32_e32 v41, 60, v8
	v_or_b32_e32 v42, 62, v8
	v_lshl_add_u64 v[4:5], s[2:3], 0, v[176:177]
	v_add3_u32 v43, s9, v7, v11
	s_lshl_b32 s10, s8, 5
	v_add_u32_e32 v44, v6, v10
	s_mov_b32 s11, s8
	v_readlane_b32 s13, v253, 24
	v_readlane_b32 s14, v253, 25
	v_readlane_b32 s15, v253, 26
	v_readlane_b32 s16, v253, 27
	v_readlane_b32 s17, v253, 28
	v_readlane_b32 s20, v253, 31
	v_readlane_b32 s21, v253, 32
	v_readlane_b32 s22, v253, 33
	v_readlane_b32 s23, v253, 34
	v_readlane_b32 s24, v253, 35
	v_readlane_b32 s25, v253, 36
	v_readlane_b32 s26, v253, 37
	v_readlane_b32 s27, v253, 38
	s_branch .LBB0_684

.LBB0_942:
	s_cmp_lg_u64 s[74:75], 0
	s_cbranch_scc1 .LBB0_945
	s_cmpk_gt_i32 s8, 0x15ff
	s_cbranch_scc1 .LBB0_945
	v_readlane_b32 s12, v253, 23
	v_readlane_b32 s2, v254, 34
	v_mov_b32_e32 v1, v177
	v_readlane_b32 s26, v254, 36
	v_readlane_b32 s27, v254, 37
	v_lshlrev_b32_e32 v176, 1, v12
	v_readlane_b32 s3, v254, 35
	v_lshl_add_u64 v[2:3], s[26:27], 0, v[0:1]
	v_add_u32_e32 v4, s9, v0
	v_mul_u32_u24_e32 v5, 0x84, v12
	v_lshl_add_u64 v[0:1], s[2:3], 0, v[176:177]
	s_mul_i32 s2, s8, 0x2c000
	v_add3_u32 v11, s9, v5, v11
	v_mov_b32_e32 v5, s2
	s_movk_i32 s2, 0x1600
	v_mad_u32_u24 v9, v9, s2, v5
	s_lshl_b32 s4, s8, 5
	v_add_u32_e32 v10, v4, v10
	v_readlane_b32 s13, v253, 24
	v_readlane_b32 s14, v253, 25
	v_readlane_b32 s15, v253, 26
	v_readlane_b32 s16, v253, 27
	v_readlane_b32 s17, v253, 28
	v_readlane_b32 s18, v253, 29
	v_readlane_b32 s19, v253, 30
	v_readlane_b32 s20, v253, 31
	v_readlane_b32 s21, v253, 32
	v_readlane_b32 s22, v253, 33
	v_readlane_b32 s23, v253, 34
	v_readlane_b32 s24, v253, 35
	v_readlane_b32 s25, v253, 36

.LBB0_1699:
	s_cmpk_gt_i32 s12, 0x15ff
	s_cbranch_scc1 .LBB0_1702
	v_readlane_b32 s4, v253, 37
	v_mov_b32_e32 v1, v177
	v_readlane_b32 s5, v253, 38
	v_lshlrev_b32_e32 v176, 1, v12
	v_add_u32_e32 v4, s8, v0
	v_lshl_add_u64 v[2:3], s[4:5], 0, v[0:1]
	v_readlane_b32 s4, v254, 9
	v_readlane_b32 s5, v254, 10
	v_mul_u32_u24_e32 v5, 0x84, v12
	v_add3_u32 v11, s8, v5, v11
	v_lshl_add_u64 v[0:1], s[4:5], 0, v[176:177]
	s_mul_i32 s4, s12, 0x2c000
	v_mov_b32_e32 v5, s4
	s_movk_i32 s4, 0x1600
	v_mad_u32_u24 v9, v9, s4, v5
	s_lshl_b32 s6, s12, 5
	v_add_u32_e32 v10, v4, v10
